# static s_setprio 1 for waves 4-7 during the two attention phases (reset to 0 at every phase start)
# baseline (speedup 1.0000x reference)
; template <int MASK> __global__ void __launch_bounds__(512, 2) mega_fwd(Args a) {
;     ...
;     for (int ph = a.ph_lo; ph < a.ph_hi; ++ph) {
;     ...
;         KA ka; ka.k = (kptr_t)__builtin_amdgcn_kernarg_segment_ptr(); asm volatile("" : "+s"(ka.k));
;         ka.ws = *(unsigned char* const __attribute__((address_space(4)))*)(ka.k + 256); float* outp = *(float* const __attribute__((address_space(4)))*)(ka.k + 248);
;         ka.outb = (unsigned char*)outp;
;         unsigned char* ws = ka.ws;
;         float* rss = (float*)(ws + WS_RSS); bf16_t* xb = (bf16_t*)(ws + WS_XB); bf16_t* Hb = (bf16_t*)(ws + WS_H);
;         for (int rep = 0; rep < ((ph == PROBE_PH) ? 2 : 1); ++rep) {
;         int kind, arg = 0;
;         switch (ph) {
;             case 0: kind = 0; break;
;             case 1: kind = 1; arg = 0; break;    case 2: kind = 2; arg = 0; break;
;             case 3: kind = 3; arg = 0; break;    case 4: kind = 4; break;   case 5: kind = 5; break;   case 6: kind = 6; break;
;             case 7: kind = 2; arg = 4; break;
;             case 8: kind = 1; arg = 1; break;    case 9: kind = 2; arg = 1; break;
;             case 10: kind = 1; arg = 2; break;   case 11: kind = 2; arg = 2; break;
;             case 12: kind = 3; arg = 1; break;   case 13: kind = 7; break;  case 14: kind = 8; break;
;             case 15: kind = 2; arg = 5; break;
;             case 16: kind = 1; arg = 3; break;   default: kind = 2; arg = 3; break;
;         }
.LBB0_24:
	v_writelane_b32 v254, s0, 61
	v_readlane_b32 s8, v253, 51
	s_mov_b64 s[4:5], 0
	v_writelane_b32 v254, s1, 62
	s_mov_b64 s[0:1], -1
	v_readlane_b32 s9, v253, 52
	v_readlane_b32 s10, v253, 53
	v_readlane_b32 s11, v253, 54
	s_setprio 0
	v_readfirstlane_b32 s100, v240
	s_nop 3
	s_lshr_b32 s100, s100, 8
	s_cmp_eq_u32 s100, 0
	s_cbranch_scc1 .Lprio_done
	s_cmp_eq_u32 s8, 5
	s_cbranch_scc1 .Lprio_set
	s_cmp_eq_u32 s8, 14
	s_cbranch_scc0 .Lprio_done
.Lprio_set:
	s_setprio 1
.Lprio_done:
	s_cmp_lt_i32 s8, 8
	s_mov_b64 s[48:49], 0
	s_mov_b64 s[6:7], 0
	s_cbranch_scc1 .LBB0_58
	v_readlane_b32 s8, v253, 51
	s_cmp_gt_i32 s8, 11
	v_readlane_b32 s9, v253, 52
	v_readlane_b32 s10, v253, 53
	v_readlane_b32 s11, v253, 54
	s_cbranch_scc0 .LBB0_41
	s_mov_b64 s[10:11], 0
	s_cmp_gt_i32 s8, 13
	s_mov_b64 s[6:7], 0
	s_cbranch_scc0 .LBB0_36
	v_writelane_b32 v255, s6, 3
	v_readlane_b32 s56, v253, 51
	s_cmp_gt_i32 s56, 14
	v_writelane_b32 v255, s7, 4
	v_readlane_b32 s57, v253, 52
	s_mov_b64 s[6:7], 0
	v_readlane_b32 s58, v253, 53
	v_readlane_b32 s59, v253, 54
	s_cbranch_scc0 .LBB0_33
	v_readlane_b32 s56, v253, 51
	s_mov_b64 s[36:37], -1
	s_mov_b64 s[8:9], 0
	s_cmp_gt_i32 s56, 15
	v_readlane_b32 s57, v253, 52
	v_readlane_b32 s58, v253, 53
	v_readlane_b32 s59, v253, 54
	s_cbranch_scc0 .LBB0_31
	v_readlane_b32 s56, v253, 51
	s_mov_b64 s[6:7], -1
	s_mov_b64 s[0:1], 0
	s_cmp_eq_u32 s56, 16
	v_readlane_b32 s57, v253, 52
	v_readlane_b32 s58, v253, 53
	v_readlane_b32 s59, v253, 54
	s_cbranch_scc0 .LBB0_31
	s_mov_b64 s[6:7], 0
	s_mov_b64 s[48:49], -1
